# SSD: next chunk's z loads issued in the current chunk's epilogue (chunk 0 before the loop); scan wait exact
# baseline (speedup 1.0000x reference)
; __device__ __forceinline__ void ssd_stream(const Frame& F, const Args& A, int sidx) {
;     ...
;     const int lane = fresh_lane(), w = F.wave, tid = fresh_tid(), r32 = lane & 31, hh = lane >> 5;
;     const int qq = (lane & 15) >> 2, pp = lane & 3, cb16 = (lane >> 4) & 1;
;     const int pairi = (sidx & 7) * 4 + (sidx >> 6), b = pairi >> 2, g = pairi & 3, hd = g * 8 + ((sidx >> 3) & 7);
;     LAS unsigned char* XT = F.lds + L_XT; LAS unsigned char* XST = F.lds + L_XST; LAS unsigned char* BT = F.lds + L_BT; LAS unsigned char* CT = F.lds + L_CT; LAS unsigned char* ST = F.lds + L_ST;
;     const float a2 = -ex2(A.in[18][hd] * LOG2E) * LOG2E;
;     const float Dsk = A.in[19][hd];
;     const int pt = w >> 2, lt = w < 4 ? w : 7 - w, nt = w & 3;
;     f32x16 st;
; #pragma unroll
;     for (int i = 0; i < 16; ++i) st[i] = 0.f;
;     const GAS unsigned char* XCg = (const GAS unsigned char*)(ws + WS_XC) + (size_t)b * SEQ_T * 3072 * 2;
;     const GAS unsigned char* XBg = (const GAS unsigned char*)(ws + WS_XBC) + (size_t)b * SEQ_T * 3072 * 2;
;     const GAS unsigned char* DTg = (const GAS unsigned char*)(ws + WS_DT) + ((size_t)b * SEQ_T * 32 + hd) * 4;
;     const GAS unsigned char* Zg = (const GAS unsigned char*)(ws + WS_Z) + (size_t)b * SEQ_T * 2048 * 2;
;     GAS unsigned char* YGg = (GAS unsigned char*)(ws + WS_YG) + (size_t)b * SEQ_T * 2048 * 2;
;     GAS unsigned char* SSQg = (GAS unsigned char*)(ws + WS_SSQ) + (size_t)b * SEQ_T * 64 * 4;
;     const unsigned xoff = (unsigned)((tid >> 3) * 3072 + hd * 64 + 8 * (tid & 7)) * 2u;
;     const unsigned boff = (unsigned)((tid >> 4) * 3072 + 2048 + g * 128 + 8 * (tid & 15)) * 2u;
;     const int xdst = (tid >> 3) * XS_ + 16 * (tid & 7), bdst = (tid >> 4) * BS_ + 16 * (tid & 15);
;     const unsigned doff = (unsigned)(2 * lane) * 128u;
;     const int hrow = 8 * w - 3 + (lane >> 3);
;     const unsigned hoff = (unsigned)(hd * 64 + 8 * (lane & 7)) * 2u;
;     LAS unsigned char* HAL = F.lds + L_HALO + w * (2 * 3 * XS_);
;     LAS float* CWL = (LAS float*)(F.lds + L_CWL);
;     if (tid < 320) CWL[tid] = tid < 256 ? A.in[15][(tid >> 6) * 3072 + hd * 64 + (tid & 63)] : A.in[16][hd * 64 + (tid & 63)];
;     const int lcol = 32 * lt + r32;
;     const unsigned zoff = (unsigned)(lcol * 2048 + hd * 64 + 32 * pt + 4 * hh) * 2u;
;     const unsigned soff = (unsigned)(lcol * 64 + hd * 2 + pt) * 4u;
.LBB0_1291:
	v_and_b32_e32 v204, 31, v5
	v_readlane_b32 s12, v254, 58
	v_readlane_b32 s14, v254, 51
	v_ashrrev_i32_e32 v20, 5, v5
	v_or_b32_e32 v205, s12, v204
	s_lshl_b32 s12, s62, 3
	s_add_i32 s12, s12, s71
	v_lshl_add_u32 v12, v205, 8, s12
	s_lshl_b64 s[12:13], s[4:5], 25
	s_add_u32 s14, s14, s12
	v_readlane_b32 s15, v254, 52
	v_lshlrev_b32_e32 v150, 2, v20
	s_addc_u32 s15, s15, s13
	v_readlane_b32 s16, v254, 53
	v_add_u32_e32 v21, s70, v150
	s_add_u32 s12, s16, s12
	v_readlane_b32 s16, v254, 54
	v_add_u32_e32 v13, s24, v21
	v_lshlrev_b32_e32 v14, 12, v205
	s_addc_u32 s13, s16, s13
	s_lshl_b64 s[16:17], s[4:5], 21
	v_readlane_b32 s5, v254, 55
	v_lshl_add_u32 v14, v13, 1, v14
	s_add_u32 s16, s5, s16
	v_readlane_b32 s5, v254, 56
	v_mad_u64_u32 v[16:17], s[18:19], v175, s86, v[4:5]
	v_mad_u64_u32 v[18:19], s[18:19], v3, s87, v[6:7]
	v_lshlrev_b32_e32 v6, 4, v10
	v_lshlrev_b32_e32 v10, 2, v5
	v_mul_lo_u32 v13, v205, s86
	v_and_b32_e32 v23, 16, v5
	s_addc_u32 s17, s5, s17
	v_and_b32_e32 v10, 12, v10
	v_add_u32_e32 v17, 0, v13
	v_mov_b32_e32 v13, v139
	v_lshl_add_u64 v[156:157], s[16:17], 0, v[12:13]
	v_or3_b32 v12, s79, v23, v10
	s_add_i32 s5, 0, 0x1f000
	v_lshl_add_u32 v209, v12, 1, 0
	v_or3_b32 v12, s70, v23, v10
	v_lshl_add_u32 v207, v9, 2, s5
	v_lshl_add_u32 v19, v12, 1, 0
	v_mul_lo_u32 v12, v7, s86
	v_readlane_b32 s5, v254, 57
	v_add_u32_e32 v25, 1, v7
	v_add_u32_e32 v4, 0, v6
	v_add3_u32 v210, s5, v6, v12
	v_add_u32_e32 v12, s73, v25
	v_mul_lo_u32 v12, v12, s86
	v_add_u32_e32 v28, 2, v7
	v_add3_u32 v27, v4, v12, s91
	v_add_u32_e32 v12, s73, v28
	v_mul_lo_u32 v12, v12, s86
	v_add_u32_e32 v25, s72, v25
	v_or_b32_e32 v3, s70, v204
	v_add3_u32 v30, v4, v12, s91
	v_add_u32_e32 v12, s82, v7
	v_mul_lo_u32 v25, v25, s86
	v_mul_lo_u32 v3, v3, s87
	v_add_u32_e32 v26, 0x90, v210
	v_mul_lo_u32 v12, v12, s86
	v_add_u32_e32 v33, 0x240, v210
	v_add3_u32 v25, v4, v25, s91
	v_add_u32_e32 v28, s72, v28
	v_cmp_lt_i32_e64 s[26:27], 1, v7
	v_add_u32_e32 v206, s3, v3
	v_mov_b32_e32 v15, v139
	v_mov_b32_e32 v3, v139
	v_mul_lo_u32 v6, v1, s86
	v_add3_u32 v32, v4, v12, s91
	v_add_u32_e32 v12, s72, v7
	v_mul_lo_u32 v28, v28, s86
	v_cndmask_b32_e64 v213, v26, v27, s[26:27]
	v_cndmask_b32_e64 v217, v33, v25, s[26:27]
	s_add_i32 s26, 0, 0x1e400
	v_bfe_u32 v22, v5, 2, 2
	v_lshl_add_u64 v[152:153], s[14:15], 0, v[14:15]
	v_lshlrev_b32_e32 v208, 4, v20
	v_lshl_add_u64 v[154:155], s[12:13], 0, v[14:15]
	v_lshlrev_b32_e32 v14, 3, v20
	v_add3_u32 v6, v4, v6, s91
	v_mad_u64_u32 v[12:13], s[14:15], v12, s86, v[4:5]
	v_add_u32_e32 v34, 0x2d0, v210
	v_add3_u32 v4, v4, v28, s91
	v_cmp_lt_i32_e64 s[28:29], 0, v7
	v_lshl_add_u32 v220, v11, 2, s26
	v_lshl_add_u64 v[176:177], s[34:35], 0, v[2:3]
	v_mul_u32_u24_e32 v2, 0x110, v204
	s_mov_b32 s26, 0x9000
	v_or_b32_e32 v15, v22, v14
	v_cndmask_b32_e64 v218, v34, v4, s[28:29]
	v_add3_u32 v221, v2, v208, s26
	s_movk_i32 s26, 0x240
	v_add_u32_e32 v4, s70, v23
	v_mul_lo_u32 v9, v205, s87
	v_mul_lo_u32 v211, v15, s87
	v_mul_lo_u32 v2, v20, s26
	v_mul_u32_u24_e32 v3, 0x90, v22
	v_add_lshl_u32 v4, v4, v10, 1
	v_add_u32_e32 v9, s90, v9
	v_add_u32_e32 v24, s2, v206
	v_add_u32_e32 v29, 0x120, v210
	v_add_u32_e32 v31, 0x1b0, v210
	v_add_u32_e32 v13, 0x4800, v12
	v_add_u32_e32 v28, 0x360, v210
	v_add_u32_e32 v12, 0x49b0, v12
	v_mad_i64_i32 v[158:159], s[14:15], v1, s0, 0
	v_mad_i64_i32 v[160:161], s[14:15], v8, s0, 0
	v_lshlrev_b32_e32 v8, 1, v21
	v_mul_lo_u32 v15, v15, s86
	v_add_u32_e32 v21, 0x1100, v211
	v_cmp_lt_i32_e32 vcc, 2, v7
	v_cmp_lt_i32_e64 s[30:31], -1, v7
	v_add3_u32 v222, v2, v3, v4
	v_mov_b32_e32 v2, 0
	v_mov_b32_e32 v149, v148
	v_cmp_gt_u32_e64 s[12:13], 32, v5
	s_mov_b32 s5, 0
	v_or_b32_e32 v1, 3, v150
	v_or_b32_e32 v162, 2, v150
	v_add_u32_e32 v151, 9, v150
	v_add_u32_e32 v164, 8, v150
	v_add_u32_e32 v163, 11, v150
	v_add_u32_e32 v166, 10, v150
	v_add_u32_e32 v165, 17, v150
	v_add_u32_e32 v168, 16, v150
	v_add_u32_e32 v167, 19, v150
	v_add_u32_e32 v170, 18, v150
	v_add_u32_e32 v169, 25, v150
	v_add_u32_e32 v172, 24, v150
	v_add_u32_e32 v171, 27, v150
	v_add_u32_e32 v174, 26, v150
	v_cmp_gt_i32_e64 s[14:15], 1, v5
	v_cmp_gt_i32_e64 s[16:17], 2, v5
	v_cmp_gt_i32_e64 s[18:19], 4, v5
	v_cmp_gt_i32_e64 s[20:21], 8, v5
	v_cmp_gt_i32_e64 s[22:23], 16, v5
	v_cmp_gt_i32_e64 s[24:25], 32, v5
	v_cndmask_b32_e32 v212, v210, v6, vcc
	v_cndmask_b32_e64 v214, v29, v30, s[28:29]
	v_cndmask_b32_e64 v215, v31, v32, s[30:31]
	v_cndmask_b32_e32 v216, v31, v13, vcc
	v_cndmask_b32_e64 v219, v28, v12, s[30:31]
	v_add_u32_e32 v223, v24, v14
	v_add_u32_e32 v224, 0, v18
	v_add_u32_e32 v225, v9, v208
	v_add_u32_e32 v226, v17, v8
	v_add_u32_e32 v227, v19, v15
	v_add_u32_e32 v228, v209, v21
	v_add_u32_e32 v229, 0, v16
	v_mov_b32_e32 v3, v2
	v_mov_b32_e32 v4, v2
	v_mov_b32_e32 v5, v2
	v_mov_b32_e32 v6, v2
	v_mov_b32_e32 v7, v2
	v_mov_b32_e32 v8, v2
	v_mov_b32_e32 v9, v2
	v_mov_b32_e32 v10, v2
	v_mov_b32_e32 v11, v2
	v_mov_b32_e32 v12, v2
	v_mov_b32_e32 v13, v2
	v_mov_b32_e32 v14, v2
	v_mov_b32_e32 v15, v2
	v_mov_b32_e32 v16, v2
	v_mov_b32_e32 v17, v2
	global_load_dwordx2 v[184:185], v[152:153], off
	global_load_dwordx2 v[182:183], v[152:153], off offset:16
	global_load_dwordx2 v[180:181], v[152:153], off offset:32
	global_load_dwordx2 v[178:179], v[152:153], off offset:48
	s_branch .LBB0_1293

; __device__ __forceinline__ unsigned cvt_pk_bf16(float lo, float hi) { unsigned r; asm volatile("v_cvt_pk_bf16_f32 %0, %1, %2" : "=v"(r) : "v"(lo), "v"(hi)); return r; }
; #define LAS __attribute__((address_space(3)))
; __device__ __forceinline__ void ssd_stream(const Frame& F, const Args& A, int sidx) {
;     ...
;         __syncthreads();
; #pragma unroll
;         for (int q4 = 0; q4 < 4; ++q4) { v2u o; o.x = pg8::cvt_pk_bf16(st[4 * q4], st[4 * q4 + 1]); o.y = pg8::cvt_pk_bf16(st[4 * q4 + 2], st[4 * q4 + 3]);
;             *(LAS v2u*)(ST + (32 * pt + r32) * BS_ + (32 * nt + 8 * q4 + 4 * hh) * 2) = o; }
;         {
;             const float aL = arr[127];
; #pragma unroll
;             for (int i = 0; i < 2; ++i) { *(LAS v4u*)(XST + xdst + 64 * i * XS_) = pfx[i]; if (lane < 24) *(LAS v4u*)(HAL + (3 * i + (lane >> 3)) * XS_ + 16 * (lane & 7)) = pfh[i]; }
.LBB0_1293:
	s_lshl_b32 s92, s5, 7
	s_lshl_b64 s[64:65], s[92:93], 12
	s_bitcmp1_b32 s5, 0
	s_waitcnt lgkmcnt(0)
	s_barrier
	v_cvt_pk_bf16_f32 v18, v2, v3
	s_cselect_b32 s66, 0x600, 0
	v_cvt_pk_bf16_f32 v19, v4, v5
	ds_write_b64 v223, v[18:19]
	v_cvt_pk_bf16_f32 v18, v6, v7
	v_cvt_pk_bf16_f32 v19, v8, v9
	ds_write_b64 v223, v[18:19] offset:16
	v_cvt_pk_bf16_f32 v18, v10, v11
	s_add_i32 s78, s66, 0
	v_cvt_pk_bf16_f32 v19, v12, v13
	ds_write_b64 v223, v[18:19] offset:32
	v_cvt_pk_bf16_f32 v18, v14, v15
	s_add_i32 s78, s78, 0x1e400
	v_cvt_pk_bf16_f32 v19, v16, v17
	ds_write_b64 v223, v[18:19] offset:48
	v_mov_b32_e32 v18, s78
	ds_read_b32 v106, v18 offset:508
	s_waitcnt vmcnt(13)
	ds_write_b128 v229, v[50:53] offset:18432
	s_and_saveexec_b64 s[26:27], s[6:7]
	s_xor_b64 s[26:27], exec, s[26:27]
	s_cbranch_execz .LBB0_1295
	s_waitcnt vmcnt(12)
	ds_write_b128 v229, v[62:65] offset:27648

; __device__ __forceinline__ unsigned cvt_pk_bf16(float lo, float hi) { unsigned r; asm volatile("v_cvt_pk_bf16_f32 %0, %1, %2" : "=v"(r) : "v"(lo), "v"(hi)); return r; }
; __device__ __forceinline__ float silu_f(float x) { return x * sigm(x); }
; #define GAS __attribute__((address_space(1)))
; #define LAS __attribute__((address_space(3)))
; __device__ __forceinline__ void ssd_stream(const Frame& F, const Args& A, int sidx) {
;     ...
;         { const GAS unsigned char* zb = Zg + (size_t)t0 * 4096;
; #pragma unroll
;           for (int q4 = 0; q4 < 4; ++q4) zw[q4] = *(const GAS v2u*)(zb + 16 * q4 + zoff); }
;     ...
;         {
;             GAS unsigned char* yb = YGg + (size_t)t0 * 4096;
;             float ssq = 0.f;
; #pragma unroll
;             for (int q4 = 0; q4 < 4; ++q4) {
;                 const int p0 = 32 * pt + 8 * q4 + 4 * hh;
;                 const v2u xw = *(LAS v2u*)(XT + lcol * XS_ + p0 * 2);
;                 const float y0 = (Y[4 * q4 + 0] + Dsk * bflo(xw.x)) * silu_f(bflo(zw[q4].x)), y1 = (Y[4 * q4 + 1] + Dsk * bfhi(xw.x)) * silu_f(bfhi(zw[q4].x));
;                 const float y2 = (Y[4 * q4 + 2] + Dsk * bflo(xw.y)) * silu_f(bflo(zw[q4].y)), y3 = (Y[4 * q4 + 3] + Dsk * bfhi(xw.y)) * silu_f(bfhi(zw[q4].y));
;                 ssq += (y0 * y0 + y1 * y1) + (y2 * y2 + y3 * y3);
;                 v2u o; o.x = pg8::cvt_pk_bf16(y0, y1); o.y = pg8::cvt_pk_bf16(y2, y3);
;                 *(GAS v2u*)(yb + 16 * q4 + zoff) = o;
;             }
;             ssq += __shfl_xor(ssq, 32);
;             if (hh == 0) *(GAS float*)(SSQg + (size_t)t0 * 256 + soff) = ssq;
.LZW_go:
	v_lshlrev_b32_e32 v98, 16, v184
	v_and_b32_e32 v99, 0xffff0000, v184
	v_lshlrev_b32_e32 v100, 16, v185
	v_and_b32_e32 v101, 0xffff0000, v185
	v_lshlrev_b32_e32 v102, 16, v182
	v_and_b32_e32 v103, 0xffff0000, v182
	v_lshlrev_b32_e32 v104, 16, v183
	v_and_b32_e32 v105, 0xffff0000, v183
	v_lshlrev_b32_e32 v106, 16, v180
	v_and_b32_e32 v107, 0xffff0000, v180
	v_lshlrev_b32_e32 v108, 16, v181
	v_and_b32_e32 v109, 0xffff0000, v181
	v_lshlrev_b32_e32 v110, 16, v178
	v_and_b32_e32 v111, 0xffff0000, v178
	v_lshlrev_b32_e32 v112, 16, v179
	v_and_b32_e32 v113, 0xffff0000, v179
	s_andn2_b64 vcc, exec, s[60:61]
	s_cbranch_vccnz .LZN_skip
	s_add_u32 s100, s64, 0x80000
	s_addc_u32 s101, s65, 0
	v_lshl_add_u64 v[198:199], v[152:153], 0, s[100:101]
	global_load_dwordx2 v[184:185], v[198:199], off
	global_load_dwordx2 v[182:183], v[198:199], off offset:16
	global_load_dwordx2 v[180:181], v[198:199], off offset:32
	global_load_dwordx2 v[178:179], v[198:199], off offset:48
.LZN_skip:
	v_mul_f32_e32 v114, 0xbfb8aa3b, v98
	v_mul_f32_e32 v115, 0xbfb8aa3b, v99
	v_mul_f32_e32 v116, 0xbfb8aa3b, v100
	v_mul_f32_e32 v117, 0xbfb8aa3b, v101
	v_mul_f32_e32 v118, 0xbfb8aa3b, v102
	v_mul_f32_e32 v119, 0xbfb8aa3b, v103
	v_mul_f32_e32 v120, 0xbfb8aa3b, v104
	v_mul_f32_e32 v121, 0xbfb8aa3b, v105
	v_mul_f32_e32 v122, 0xbfb8aa3b, v106
	v_mul_f32_e32 v123, 0xbfb8aa3b, v107
	v_mul_f32_e32 v124, 0xbfb8aa3b, v108
	v_mul_f32_e32 v125, 0xbfb8aa3b, v109
	v_mul_f32_e32 v126, 0xbfb8aa3b, v110
	v_mul_f32_e32 v127, 0xbfb8aa3b, v111
	v_mul_f32_e32 v128, 0xbfb8aa3b, v112
	v_mul_f32_e32 v129, 0xbfb8aa3b, v113
	v_exp_f32_e32 v114, v114
	v_exp_f32_e32 v115, v115
	v_exp_f32_e32 v116, v116
	v_exp_f32_e32 v117, v117
	v_exp_f32_e32 v118, v118
	v_exp_f32_e32 v119, v119
	v_exp_f32_e32 v120, v120
	v_exp_f32_e32 v121, v121
	v_exp_f32_e32 v122, v122
	v_exp_f32_e32 v123, v123
	v_exp_f32_e32 v124, v124
	v_exp_f32_e32 v125, v125
	v_exp_f32_e32 v126, v126
	v_exp_f32_e32 v127, v127
	v_exp_f32_e32 v128, v128
	v_exp_f32_e32 v129, v129
	s_waitcnt lgkmcnt(0)
	v_lshlrev_b32_e32 v186, 16, v36
	v_and_b32_e32 v187, 0xffff0000, v36
	v_lshlrev_b32_e32 v188, 16, v37
	v_and_b32_e32 v189, 0xffff0000, v37
	v_lshlrev_b32_e32 v190, 16, v38
	v_and_b32_e32 v191, 0xffff0000, v38
	v_lshlrev_b32_e32 v192, 16, v39
	v_and_b32_e32 v193, 0xffff0000, v39
	v_lshlrev_b32_e32 v194, 16, v40
	v_and_b32_e32 v195, 0xffff0000, v40
	v_lshlrev_b32_e32 v196, 16, v41
	v_and_b32_e32 v197, 0xffff0000, v41
	v_lshlrev_b32_e32 v198, 16, v42
	v_and_b32_e32 v199, 0xffff0000, v42
	v_lshlrev_b32_e32 v200, 16, v43
	v_and_b32_e32 v201, 0xffff0000, v43
	v_add_f32_e32 v114, 1.0, v114
	v_add_f32_e32 v115, 1.0, v115
	v_add_f32_e32 v116, 1.0, v116
	v_add_f32_e32 v117, 1.0, v117
	v_add_f32_e32 v118, 1.0, v118
	v_add_f32_e32 v119, 1.0, v119
	v_add_f32_e32 v120, 1.0, v120
	v_add_f32_e32 v121, 1.0, v121
	v_add_f32_e32 v122, 1.0, v122
	v_add_f32_e32 v123, 1.0, v123
	v_add_f32_e32 v124, 1.0, v124
	v_add_f32_e32 v125, 1.0, v125
	v_add_f32_e32 v126, 1.0, v126
	v_add_f32_e32 v127, 1.0, v127
	v_add_f32_e32 v128, 1.0, v128
	v_add_f32_e32 v129, 1.0, v129
	v_rcp_f32_e32 v114, v114
	v_rcp_f32_e32 v115, v115
	v_rcp_f32_e32 v116, v116
	v_rcp_f32_e32 v117, v117
	v_rcp_f32_e32 v118, v118
	v_rcp_f32_e32 v119, v119
	v_rcp_f32_e32 v120, v120
	v_rcp_f32_e32 v121, v121
	v_rcp_f32_e32 v122, v122
	v_rcp_f32_e32 v123, v123
	v_rcp_f32_e32 v124, v124
	v_rcp_f32_e32 v125, v125
	v_rcp_f32_e32 v126, v126
	v_rcp_f32_e32 v127, v127
	v_rcp_f32_e32 v128, v128
	v_rcp_f32_e32 v129, v129
	v_pk_mul_f32 v[186:187], v[186:187], v[44:45]
	v_pk_mul_f32 v[188:189], v[188:189], v[44:45]
	v_pk_mul_f32 v[190:191], v[190:191], v[44:45]
	v_pk_mul_f32 v[192:193], v[192:193], v[44:45]
	v_pk_mul_f32 v[194:195], v[194:195], v[44:45]
	v_pk_mul_f32 v[196:197], v[196:197], v[44:45]
	v_pk_mul_f32 v[198:199], v[198:199], v[44:45]
	v_pk_mul_f32 v[200:201], v[200:201], v[44:45]
	v_pk_mul_f32 v[114:115], v[114:115], v[98:99]
	v_pk_mul_f32 v[116:117], v[116:117], v[100:101]
	v_pk_mul_f32 v[118:119], v[118:119], v[102:103]
	v_pk_mul_f32 v[120:121], v[120:121], v[104:105]
	v_pk_mul_f32 v[122:123], v[122:123], v[106:107]
	v_pk_mul_f32 v[124:125], v[124:125], v[108:109]
	v_pk_mul_f32 v[126:127], v[126:127], v[110:111]
	v_pk_mul_f32 v[128:129], v[128:129], v[112:113]
	v_pk_add_f32 v[18:19], v[18:19], v[186:187]
	v_pk_add_f32 v[20:21], v[20:21], v[188:189]
	v_pk_add_f32 v[22:23], v[22:23], v[190:191]
	v_pk_add_f32 v[24:25], v[24:25], v[192:193]
	v_pk_add_f32 v[26:27], v[26:27], v[194:195]
	v_pk_add_f32 v[28:29], v[28:29], v[196:197]
	v_pk_add_f32 v[30:31], v[30:31], v[198:199]
	v_pk_add_f32 v[32:33], v[32:33], v[200:201]
	v_pk_mul_f32 v[18:19], v[114:115], v[18:19]
	v_pk_mul_f32 v[20:21], v[116:117], v[20:21]
	v_pk_mul_f32 v[22:23], v[118:119], v[22:23]
	v_pk_mul_f32 v[24:25], v[120:121], v[24:25]
	v_pk_mul_f32 v[26:27], v[122:123], v[26:27]
	v_pk_mul_f32 v[28:29], v[124:125], v[28:29]
	v_pk_mul_f32 v[30:31], v[126:127], v[30:31]
	v_pk_mul_f32 v[32:33], v[128:129], v[32:33]
	v_cvt_pk_bf16_f32 v232, v18, v19
	v_cvt_pk_bf16_f32 v233, v20, v21
	v_cvt_pk_bf16_f32 v234, v22, v23
	v_cvt_pk_bf16_f32 v235, v24, v25
	v_cvt_pk_bf16_f32 v236, v26, v27
	v_cvt_pk_bf16_f32 v237, v28, v29
	v_cvt_pk_bf16_f32 v238, v30, v31
	v_cvt_pk_bf16_f32 v239, v32, v33
	v_mul_f32_e32 v130, v19, v19
	v_mul_f32_e32 v46, v21, v21
	v_mul_f32_e32 v131, v23, v23
	v_mul_f32_e32 v47, v25, v25
	v_mul_f32_e32 v132, v27, v27
	v_mul_f32_e32 v40, v29, v29
	v_mul_f32_e32 v133, v31, v31
	v_mul_f32_e32 v41, v33, v33
	v_fmac_f32_e32 v130, v18, v18
	v_fmac_f32_e32 v46, v20, v20
	v_fmac_f32_e32 v131, v22, v22
	v_fmac_f32_e32 v47, v24, v24
	v_fmac_f32_e32 v132, v26, v26
	v_fmac_f32_e32 v40, v28, v28
	v_fmac_f32_e32 v133, v30, v30
	v_fmac_f32_e32 v41, v32, v32
	v_add_f32_e32 v130, v130, v46
	v_add_f32_e32 v131, v131, v47
	v_add_f32_e32 v132, v132, v40
	v_add_f32_e32 v133, v133, v41
	v_permlane32_swap_b32_e32 v232, v234
	v_permlane32_swap_b32_e32 v233, v235
	v_permlane32_swap_b32_e32 v236, v238
	v_permlane32_swap_b32_e32 v237, v239
	v_add_f32_e32 v24, v130, v131
	v_add_f32_e32 v24, v24, v132
	v_mov_b32_e32 v19, v133
	global_store_dwordx4 v[34:35], v[232:235], off
	global_store_dwordx4 v[34:35], v[236:239], off offset:32
	v_and_b32_e32 v18, 64, v202
	v_xor_b32_e32 v20, 32, v202
	v_add_u32_e32 v21, 64, v18
	v_cmp_lt_i32_e32 vcc, v20, v21
	v_add_f32_e32 v19, v24, v19
	s_nop 0
	v_cndmask_b32_e32 v20, v202, v20, vcc
	v_lshlrev_b32_e32 v20, 2, v20
	ds_bpermute_b32 v20, v20, v19
	s_and_saveexec_b64 s[26:27], s[12:13]
	s_cbranch_execz .LBB0_1314
	s_lshl_b64 s[28:29], s[92:93], 8
	v_lshl_add_u64 v[22:23], v[156:157], 0, s[28:29]
	s_waitcnt lgkmcnt(0)
	v_add_f32_e32 v19, v19, v20
	global_store_dword v[22:23], v19, off
; __device__ __forceinline__ float ex2(float x) { return __builtin_amdgcn_exp2f(x); }
; #define LAS __attribute__((address_space(3)))
; __device__ __forceinline__ s16x4 trr(LAS unsigned char* p) { return __builtin_bit_cast(s16x4, __builtin_amdgcn_ds_read_tr16_b64_v4i16((LAS v4i16_t*)p)); }
; __device__ __forceinline__ bf16x8 cat8(s16x4 lo, s16x4 hi) { return (bf16x8){lo[0], lo[1], lo[2], lo[3], hi[0], hi[1], hi[2], hi[3]}; }
; #define MFMA32(a, b, c) __builtin_amdgcn_mfma_f32_32x32x16_bf16((a), (b), (c), 0, 0, 0)
; __device__ __forceinline__ void ssd_stream(const Frame& F, const Args& A, int sidx) {
;     ...
;         {
;             const float eL = ex2(arr[127]);
; #pragma unroll
;             for (int i = 0; i < 16; ++i) st[i] *= eL;
; #pragma unroll
;             for (int kg = 0; kg < 2; ++kg) {
;                 s16x4 alo[4], ahi[4], blo[4], bhi[4];
; #pragma unroll
;                 for (int k4 = 0; k4 < 4; ++k4) { const int ks = 4 * kg + k4;
;                     LAS unsigned char* ba = BT + (16 * ks + 8 * hh + qq) * BS_ + (32 * nt + 16 * cb16 + 4 * pp) * 2;
;                     LAS unsigned char* xa = XST + (16 * ks + 8 * hh + qq) * XS_ + (32 * pt + 16 * cb16 + 4 * pp) * 2;
;                     alo[k4] = trr(ba); ahi[k4] = trr(ba + 4 * BS_); blo[k4] = trr(xa); bhi[k4] = trr(xa + 4 * XS_); }
;                 __builtin_amdgcn_sched_barrier(0);
; #pragma unroll
;                 for (int k4 = 0; k4 < 4; ++k4) st = MFMA32(cat8(alo[k4], ahi[k4]), cat8(blo[k4], bhi[k4]), st);
;             }
;         }
;         if (ck < 63) SSD_SCAN((LAS float*)(F.lds + L_ARR + ((ck + 1) & 1) * 1536));
.LBB0_1314:
	s_or_b64 exec, exec, s[26:27]
	v_mov_b32_e32 v19, s78
	ds_read_b32 v19, v19 offset:508
	s_waitcnt lgkmcnt(0)
	v_exp_f32_e32 v20, v19
	v_add_u32_e32 v19, v209, v211
	v_pk_mul_f32 v[16:17], v[16:17], v[20:21] op_sel_hi:[1,0]
	v_pk_mul_f32 v[14:15], v[14:15], v[20:21] op_sel_hi:[1,0]
	v_pk_mul_f32 v[12:13], v[12:13], v[20:21] op_sel_hi:[1,0]
	v_pk_mul_f32 v[10:11], v[10:11], v[20:21] op_sel_hi:[1,0]
	v_pk_mul_f32 v[8:9], v[8:9], v[20:21] op_sel_hi:[1,0]
	v_pk_mul_f32 v[6:7], v[6:7], v[20:21] op_sel_hi:[1,0]
	v_pk_mul_f32 v[4:5], v[4:5], v[20:21] op_sel_hi:[1,0]
	v_pk_mul_f32 v[2:3], v[2:3], v[20:21] op_sel_hi:[1,0]
	ds_read_b64_tr_b16 v[20:21], v19 offset:36864
	ds_read_b64_tr_b16 v[22:23], v19 offset:37952
	ds_read_b64_tr_b16 v[24:25], v227 offset:18432
	ds_read_b64_tr_b16 v[26:27], v227 offset:19008
	ds_read_b64_tr_b16 v[28:29], v19 offset:41216
	ds_read_b64_tr_b16 v[30:31], v19 offset:42304
	ds_read_b64_tr_b16 v[32:33], v227 offset:20736
	ds_read_b64_tr_b16 v[34:35], v227 offset:21312
	ds_read_b64_tr_b16 v[36:37], v19 offset:45568
	ds_read_b64_tr_b16 v[38:39], v19 offset:46656
	ds_read_b64_tr_b16 v[40:41], v227 offset:23040
	ds_read_b64_tr_b16 v[42:43], v227 offset:23616
	ds_read_b64_tr_b16 v[44:45], v19 offset:49920
	ds_read_b64_tr_b16 v[46:47], v19 offset:51008
	ds_read_b64_tr_b16 v[98:99], v227 offset:25344
	ds_read_b64_tr_b16 v[100:101], v227 offset:25920
	s_waitcnt lgkmcnt(12)
	v_mfma_f32_32x32x16_bf16 v[2:17], v[20:23], v[24:27], v[2:17]
	s_waitcnt lgkmcnt(8)
	v_mfma_f32_32x32x16_bf16 v[2:17], v[28:31], v[32:35], v[2:17]
	s_waitcnt lgkmcnt(4)
	v_mfma_f32_32x32x16_bf16 v[2:17], v[36:39], v[40:43], v[2:17]
	s_waitcnt lgkmcnt(0)
	v_mfma_f32_32x32x16_bf16 v[2:17], v[44:47], v[98:101], v[2:17]
	ds_read_b64_tr_b16 v[20:21], v19 offset:54272
	ds_read_b64_tr_b16 v[22:23], v19 offset:55360
	ds_read_b64_tr_b16 v[24:25], v227 offset:27648
	ds_read_b64_tr_b16 v[26:27], v227 offset:28224
	ds_read_b64_tr_b16 v[28:29], v19 offset:58624
	ds_read_b64_tr_b16 v[30:31], v19 offset:59712
	ds_read_b64_tr_b16 v[32:33], v227 offset:29952
	ds_read_b64_tr_b16 v[34:35], v227 offset:30528
	ds_read_b64_tr_b16 v[36:37], v19 offset:62976
	ds_read_b64_tr_b16 v[38:39], v19 offset:64064
	ds_read_b64_tr_b16 v[40:41], v227 offset:32256
	ds_read_b64_tr_b16 v[42:43], v227 offset:32832
	ds_read_b64_tr_b16 v[44:45], v228 offset:62976
	ds_read_b64_tr_b16 v[46:47], v228 offset:64064
	ds_read_b64_tr_b16 v[98:99], v227 offset:34560
	ds_read_b64_tr_b16 v[100:101], v227 offset:35136
	s_waitcnt lgkmcnt(12)
	v_mfma_f32_32x32x16_bf16 v[2:17], v[20:23], v[24:27], v[2:17]
	s_and_b64 s[26:27], s[96:97], s[60:61]
	s_andn2_b64 vcc, exec, s[26:27]
	s_waitcnt lgkmcnt(8)
	v_mfma_f32_32x32x16_bf16 v[2:17], v[28:31], v[32:35], v[2:17]
	s_waitcnt lgkmcnt(4)
	v_mfma_f32_32x32x16_bf16 v[2:17], v[36:39], v[40:43], v[2:17]
	s_waitcnt lgkmcnt(0)
	v_mfma_f32_32x32x16_bf16 v[2:17], v[44:47], v[98:101], v[2:17]
	s_cbranch_vccnz .LBB0_1292
	s_waitcnt vmcnt(7)
	v_pk_mul_f32 v[20:21], v[148:149], v[146:147]
	v_add_u32_e32 v22, -2, v202
	v_add_f32_e32 v19, v21, v20
	v_add_u32_e32 v20, -1, v202
	v_cmp_lt_i32_e32 vcc, v20, v18
	s_andn2_b32 s26, 1, s5
	s_mulk_i32 s26, 0x600
	v_cndmask_b32_e32 v20, v20, v202, vcc
	v_lshlrev_b32_e32 v20, 2, v20
	ds_bpermute_b32 v20, v20, v19
	v_cmp_lt_i32_e32 vcc, v22, v18
	s_waitcnt lgkmcnt(0)
	v_add_f32_e32 v20, v19, v20
	v_cndmask_b32_e64 v19, v20, v19, s[14:15]
	v_cndmask_b32_e32 v20, v22, v202, vcc
	v_lshlrev_b32_e32 v20, 2, v20
	ds_bpermute_b32 v20, v20, v19
	v_add_u32_e32 v22, -4, v202
	v_cmp_lt_i32_e32 vcc, v22, v18
	s_waitcnt lgkmcnt(0)
	v_add_f32_e32 v20, v19, v20
	v_cndmask_b32_e64 v19, v20, v19, s[16:17]
	v_cndmask_b32_e32 v20, v22, v202, vcc
	v_lshlrev_b32_e32 v20, 2, v20
	ds_bpermute_b32 v20, v20, v19
	v_add_u32_e32 v22, -8, v202
	v_cmp_lt_i32_e32 vcc, v22, v18
	s_waitcnt lgkmcnt(0)
	v_add_f32_e32 v20, v19, v20
	v_cndmask_b32_e64 v19, v20, v19, s[18:19]
	v_cndmask_b32_e32 v20, v22, v202, vcc
	v_lshlrev_b32_e32 v20, 2, v20
	ds_bpermute_b32 v20, v20, v19
	v_add_u32_e32 v22, -16, v202
	v_cmp_lt_i32_e32 vcc, v22, v18
	s_waitcnt lgkmcnt(0)
	v_add_f32_e32 v20, v19, v20
	v_cndmask_b32_e64 v19, v20, v19, s[20:21]
	v_cndmask_b32_e32 v20, v22, v202, vcc
	v_lshlrev_b32_e32 v20, 2, v20
	ds_bpermute_b32 v20, v20, v19
	v_subrev_u32_e32 v22, 32, v202
	v_cmp_lt_i32_e32 vcc, v22, v18
	v_add_lshl_u32 v18, v18, v203, 2
	s_waitcnt lgkmcnt(0)
	v_add_f32_e32 v20, v19, v20
	v_cndmask_b32_e64 v19, v20, v19, s[22:23]
	v_cndmask_b32_e32 v20, v22, v202, vcc
	v_lshlrev_b32_e32 v20, 2, v20
	ds_bpermute_b32 v20, v20, v19
	s_waitcnt lgkmcnt(0)
	v_add_f32_e32 v20, v19, v20
	v_cndmask_b32_e64 v19, v20, v19, s[24:25]
	ds_bpermute_b32 v20, v18, v19
	v_sub_f32_e32 v18, v19, v21
	s_waitcnt lgkmcnt(0)
	v_sub_f32_e32 v21, v20, v18
	v_sub_f32_e32 v22, v20, v19
	v_exp_f32_e32 v20, v21
	v_exp_f32_e32 v21, v22
	v_add_u32_e32 v22, s26, v220
	ds_write2st64_b64 v22, v[18:19], v[146:147] offset1:1
	v_pk_mul_f32 v[18:19], v[146:147], v[20:21]
	ds_write_b64 v22, v[18:19] offset:1024
	s_branch .LBB0_1292
